# retention core stage A: counted waits made exact for the steady state (vmcnt 15) with an extra first-chunk wait (vmcnt 7), so the q/k group waits no longer force the previous chunk's O stores to retir
# baseline (speedup 1.0000x reference)
; #define LAS __attribute__((address_space(3)))
; #define GAS __attribute__((address_space(1)))
; __device__ __forceinline__ bf16_t f2bf(float x) { return (bf16_t)(cvt_pk_bf16(x, x) & 0xffffu); }
; __device__ __forceinline__ float bf2f(bf16_t v) { return __uint_as_float((unsigned)v << 16); }
; __device__ __forceinline__ u32x4 pack8(const float* v) { u32x4 w; w.x = cvt_pk_bf16(v[0], v[1]); w.y = cvt_pk_bf16(v[2], v[3]); w.z = cvt_pk_bf16(v[4], v[5]); w.w = cvt_pk_bf16(v[6], v[7]); return w; }
; #define GLA_BAR() do { asm volatile("s_waitcnt lgkmcnt(0)" ::: "memory"); __builtin_amdgcn_s_barrier(); asm volatile("" ::: "memory"); } while (0)
; template <int DK, int DVS, bool RET> ...
;     ...
;         GLA_BAR();
;         {
; #pragma unroll
;             for (int t = 0; t < TPW; ++t)
; #pragma unroll
;                 for (int j = 0; j < 4; ++j) STB[(tv * 16 + quad * 4 + j) * LK + (kt0 + t) * 16 + l16] = f2bf(st[t][j]);
;             { const int p = tid >> 3, vg = tid & 7; const long row = R0 + (dir ? 63 - p : p); vraw = *(const GAS vvec_t*)(Vg + row * ldv + vcol0 + vg * VPT); }
;             float bl;
;             if constexpr (RET) {
;                 static_assert(!RET || DK == 256, "retention prep: 64 x 256 = 2048 eight-wide items, four per thread");
;                 bl = 64.f * lg;
; #pragma unroll
;                 for (int j = 0; j < 4; ++j) { const int it = tid + 512 * j, p = it & 63, k0 = (it >> 6) * 8; const float bb = (float)(p + 1) * lg;
;                     const float eq = __expf(bb), ek = __expf(-bb); float a[8], c[8];
; #pragma unroll
;                     for (int e = 0; e < 8; ++e) { a[e] = bf2f((bf16_t)qv[j][e]) * eq; c[e] = bf2f((bf16_t)kv[j][e]) * ek; }
;                     *(LAS u32x4*)(QD + p * LK + k0) = pack8(a); *(LAS u32x4*)(KD + p * LK + k0) = pack8(c); }
.LBB0_71:
	s_cmp_gt_u32 s45, 3
	s_cselect_b32 s30, 0x47, 3
	s_add_i32 s36, s30, s42
	s_and_b64 s[30:31], s[22:23], exec
	s_cselect_b32 s30, s45, s36
	s_lshl_b32 s30, s30, 6
	s_ashr_i32 s31, s30, 31
	s_add_u32 s30, s44, s30
	s_addc_u32 s31, s43, s31
	v_lshl_add_u64 v[214:215], s[30:31], 0, v[96:97]
	v_lshlrev_b64 v[214:215], 12, v[214:215]
	v_lshl_add_u64 v[214:215], v[98:99], 0, v[214:215]
	global_load_dwordx4 v[212:215], v[214:215], off
	s_add_i32 s39, s45, 1
	s_min_i32 s39, s39, 0x43
	s_cmp_gt_u32 s39, 3
	s_cselect_b32 s38, 0x47, 3
	s_sub_i32 s38, s38, s39
	s_and_b64 s[54:55], s[22:23], exec
	s_cselect_b32 s38, s39, s38
	s_lshl_b32 s38, s38, 6
	s_add_u32 s38, s44, s38
	s_addc_u32 s39, s43, 0
	s_lshl_b64 s[38:39], s[38:39], 11
	s_add_u32 s54, s24, s38
	s_addc_u32 s55, s25, s39
	s_add_u32 s38, s28, s38
	s_addc_u32 s39, s29, s39
	s_waitcnt lgkmcnt(0)
	s_barrier
	v_cvt_pk_bf16_f32 v64, v56, v57
	v_cvt_pk_bf16_f32 v65, v58, v59
	ds_write_b64 v210, v[64:65]
	s_cmp_gt_u32 s45, 3
	s_cselect_b32 s30, 0x47, 3
	v_cvt_pk_bf16_f32 v66, v60, v61
	v_cvt_pk_bf16_f32 v67, v62, v63
	ds_write_b64 v210, v[66:67] offset:32
	s_add_i32 s36, s30, s42
	s_and_b64 s[30:31], s[22:23], exec
	v_cvt_pk_bf16_f32 v64, v48, v49
	v_cvt_pk_bf16_f32 v65, v50, v51
	ds_write_b64 v210, v[64:65] offset:64
	s_cselect_b32 s30, s45, s36
	s_lshl_b32 s30, s30, 6
	v_cvt_pk_bf16_f32 v66, v52, v53
	v_cvt_pk_bf16_f32 v67, v54, v55
	ds_write_b64 v210, v[66:67] offset:96
	s_ashr_i32 s31, s30, 31
	s_add_u32 s30, s44, s30
	v_cvt_pk_bf16_f32 v64, v40, v41
	v_cvt_pk_bf16_f32 v65, v42, v43
	ds_write_b64 v210, v[64:65] offset:128
	s_addc_u32 s31, s43, s31
	v_cvt_pk_bf16_f32 v66, v44, v45
	v_cvt_pk_bf16_f32 v67, v46, v47
	ds_write_b64 v210, v[66:67] offset:160
	v_cvt_pk_bf16_f32 v64, v36, v37
	v_cvt_pk_bf16_f32 v65, v38, v39
	ds_write_b64 v210, v[64:65] offset:192
	v_cvt_pk_bf16_f32 v66, v0, v1
	v_cvt_pk_bf16_f32 v67, v2, v3
	ds_write_b64 v210, v[66:67] offset:224
	s_waitcnt vmcnt(15)
	s_cmp_lg_u32 s45, 0
	s_cbranch_scc1 .Lret_x0
	s_waitcnt vmcnt(7)

; #define LAS __attribute__((address_space(3)))
; __device__ __forceinline__ bf16_t f2bf(float x) { return (bf16_t)(cvt_pk_bf16(x, x) & 0xffffu); }
; __device__ __forceinline__ float bf2f(bf16_t v) { return __uint_as_float((unsigned)v << 16); }
; __device__ __forceinline__ u32x4 pack8(const float* v) { u32x4 w; w.x = cvt_pk_bf16(v[0], v[1]); w.y = cvt_pk_bf16(v[2], v[3]); w.z = cvt_pk_bf16(v[4], v[5]); w.w = cvt_pk_bf16(v[6], v[7]); return w; }
; #define GLA_BAR() do { asm volatile("s_waitcnt lgkmcnt(0)" ::: "memory"); __builtin_amdgcn_s_barrier(); asm volatile("" ::: "memory"); } while (0)
; template <int DK, int DVS, bool RET> ...
;     ...
;                 bl = 64.f * lg;
; #pragma unroll
;                 for (int j = 0; j < 4; ++j) { const int it = tid + 512 * j, p = it & 63, k0 = (it >> 6) * 8; const float bb = (float)(p + 1) * lg;
;                     const float eq = __expf(bb), ek = __expf(-bb); float a[8], c[8];
; #pragma unroll
;                     for (int e = 0; e < 8; ++e) { a[e] = bf2f((bf16_t)qv[j][e]) * eq; c[e] = bf2f((bf16_t)kv[j][e]) * ek; }
;                     *(LAS u32x4*)(QD + p * LK + k0) = pack8(a); *(LAS u32x4*)(KD + p * LK + k0) = pack8(c); }
;             } else {
;                 float c = 0.f;
; #pragma unroll
;                 for (int i = 0; i < PPT; ++i) c += lc[i];
;                 TOT[pg * 128 + kx] = c;
;                 GLA_BAR();
;                 float off = 0.f; bl = 0.f;
; #pragma unroll
;                 for (int g = 0; g < NPG; ++g) { const float t = TOT[g * 128 + kx]; if (g < pg) off += t; bl += t; }
;                 float bb = off;
; #pragma unroll
;                 for (int i = 0; i < PPT; ++i) { const int p = pg * PPT + i;
;                     const float qf = bf2f(qr[i]), kf = 1.f - __expf(lc[i]); bb += lc[i];
;                     QD[p * LK + kx] = f2bf(qf * __expf(bb)); KD[p * LK + kx] = f2bf(kf * __expf(-bb)); }
;             }
;             if (pg == 0) EL[kx] = __expf(bl);
;             { const int p = tid >> 3, vg = tid & 7; *(LAS vvec_t*)(VI + p * LV + vg * VPT) = vraw; }
;         }
;         if (step + 1 < 68) GLA_LOAD(step + 1);
.Lret_x1:
	v_and_b32_e32 v231, 0xffff0000, v16
	v_lshlrev_b32_e32 v230, 16, v16
	v_and_b32_e32 v229, 0xffff0000, v12
	v_lshlrev_b32_e32 v228, 16, v12
	v_pk_mul_f32 v[232:233], v[102:103], v[230:231]
	v_and_b32_e32 v231, 0xffff0000, v13
	v_lshlrev_b32_e32 v230, 16, v13
	v_and_b32_e32 v237, 0xffff0000, v14
	v_lshlrev_b32_e32 v236, 16, v14
	v_and_b32_e32 v241, 0xffff0000, v15
	v_lshlrev_b32_e32 v240, 16, v15
	v_pk_mul_f32 v[228:229], v[100:101], v[228:229]
	v_pk_mul_f32 v[230:231], v[100:101], v[230:231]
	v_and_b32_e32 v235, 0xffff0000, v17
	v_lshlrev_b32_e32 v234, 16, v17
	v_pk_mul_f32 v[236:237], v[100:101], v[236:237]
	v_and_b32_e32 v239, 0xffff0000, v18
	v_lshlrev_b32_e32 v238, 16, v18
	v_pk_mul_f32 v[240:241], v[100:101], v[240:241]
	v_and_b32_e32 v243, 0xffff0000, v19
	v_lshlrev_b32_e32 v242, 16, v19
	global_load_dwordx4 v[12:15], v88, s[38:39]
	global_load_dwordx4 v[16:19], v88, s[54:55]
	v_pk_mul_f32 v[234:235], v[102:103], v[234:235]
	v_pk_mul_f32 v[238:239], v[102:103], v[238:239]
	v_pk_mul_f32 v[242:243], v[102:103], v[242:243]
	v_cvt_pk_bf16_f32 v228, v228, v229
	v_cvt_pk_bf16_f32 v229, v230, v231
	v_cvt_pk_bf16_f32 v230, v236, v237
	v_cvt_pk_bf16_f32 v231, v240, v241
	ds_write_b128 v180, v[228:231]
	v_cvt_pk_bf16_f32 v228, v232, v233
	v_cvt_pk_bf16_f32 v229, v234, v235
	v_cvt_pk_bf16_f32 v230, v238, v239
	v_cvt_pk_bf16_f32 v231, v242, v243
	ds_write_b128 v181, v[228:231]
	s_waitcnt vmcnt(15)
	s_cmp_lg_u32 s45, 0
	s_cbranch_scc1 .Lret_x2
	s_waitcnt vmcnt(7)
.Lret_x2:
	v_and_b32_e32 v231, 0xffff0000, v24
	v_lshlrev_b32_e32 v230, 16, v24
	v_and_b32_e32 v229, 0xffff0000, v20
	v_lshlrev_b32_e32 v228, 16, v20
	v_pk_mul_f32 v[232:233], v[102:103], v[230:231]
	v_and_b32_e32 v231, 0xffff0000, v21
	v_lshlrev_b32_e32 v230, 16, v21
	v_and_b32_e32 v237, 0xffff0000, v22
	v_lshlrev_b32_e32 v236, 16, v22
	v_and_b32_e32 v241, 0xffff0000, v23
	v_lshlrev_b32_e32 v240, 16, v23
	v_pk_mul_f32 v[228:229], v[100:101], v[228:229]
	v_pk_mul_f32 v[230:231], v[100:101], v[230:231]
	v_and_b32_e32 v235, 0xffff0000, v25
	v_lshlrev_b32_e32 v234, 16, v25
	v_pk_mul_f32 v[236:237], v[100:101], v[236:237]
	v_and_b32_e32 v239, 0xffff0000, v26
	v_lshlrev_b32_e32 v238, 16, v26
	v_pk_mul_f32 v[240:241], v[100:101], v[240:241]
	v_and_b32_e32 v243, 0xffff0000, v27
	v_lshlrev_b32_e32 v242, 16, v27
	global_load_dwordx4 v[20:23], v90, s[38:39]
	global_load_dwordx4 v[24:27], v90, s[54:55]
	v_pk_mul_f32 v[234:235], v[102:103], v[234:235]
	v_pk_mul_f32 v[238:239], v[102:103], v[238:239]
	v_pk_mul_f32 v[242:243], v[102:103], v[242:243]
	v_cvt_pk_bf16_f32 v228, v228, v229
	v_cvt_pk_bf16_f32 v229, v230, v231
	v_cvt_pk_bf16_f32 v230, v236, v237
	v_cvt_pk_bf16_f32 v231, v240, v241
	ds_write_b128 v182, v[228:231]
	v_cvt_pk_bf16_f32 v228, v232, v233
	v_cvt_pk_bf16_f32 v229, v234, v235
	v_cvt_pk_bf16_f32 v230, v238, v239
	v_cvt_pk_bf16_f32 v231, v242, v243
	ds_write_b128 v183, v[228:231]
	s_waitcnt vmcnt(15)
	s_cmp_lg_u32 s45, 0
	s_cbranch_scc1 .Lret_x3
	s_waitcnt vmcnt(7)
.Lret_x3:
	v_and_b32_e32 v231, 0xffff0000, v32
	v_lshlrev_b32_e32 v230, 16, v32
	v_and_b32_e32 v229, 0xffff0000, v28
	v_lshlrev_b32_e32 v228, 16, v28
	v_pk_mul_f32 v[232:233], v[102:103], v[230:231]
	v_and_b32_e32 v231, 0xffff0000, v29
	v_lshlrev_b32_e32 v230, 16, v29
	v_and_b32_e32 v237, 0xffff0000, v30
	v_lshlrev_b32_e32 v236, 16, v30
	v_and_b32_e32 v241, 0xffff0000, v31
	v_lshlrev_b32_e32 v240, 16, v31
	v_pk_mul_f32 v[228:229], v[100:101], v[228:229]
	v_pk_mul_f32 v[230:231], v[100:101], v[230:231]
	v_and_b32_e32 v235, 0xffff0000, v33
	v_lshlrev_b32_e32 v234, 16, v33
	v_pk_mul_f32 v[236:237], v[100:101], v[236:237]
	v_and_b32_e32 v239, 0xffff0000, v34
	v_lshlrev_b32_e32 v238, 16, v34
	v_pk_mul_f32 v[240:241], v[100:101], v[240:241]
	v_and_b32_e32 v243, 0xffff0000, v35
	v_lshlrev_b32_e32 v242, 16, v35
	global_load_dwordx4 v[28:31], v92, s[38:39]
	global_load_dwordx4 v[32:35], v92, s[54:55]
	v_pk_mul_f32 v[234:235], v[102:103], v[234:235]
	v_pk_mul_f32 v[238:239], v[102:103], v[238:239]
	v_pk_mul_f32 v[242:243], v[102:103], v[242:243]
	v_cvt_pk_bf16_f32 v228, v228, v229
	v_cvt_pk_bf16_f32 v229, v230, v231
	v_cvt_pk_bf16_f32 v230, v236, v237
	v_cvt_pk_bf16_f32 v231, v240, v241
	ds_write_b128 v184, v[228:231]
	v_cvt_pk_bf16_f32 v228, v232, v233
	v_cvt_pk_bf16_f32 v229, v234, v235
	v_cvt_pk_bf16_f32 v230, v238, v239
	v_cvt_pk_bf16_f32 v231, v242, v243
	ds_write_b128 v185, v[228:231]
	s_and_saveexec_b64 s[40:41], vcc
	ds_write_b32 v171, v173
	s_or_b64 exec, exec, s[40:41]
	s_add_i32 s36, s45, 1
	s_cmpk_eq_i32 s42, 0xffbd
	s_waitcnt vmcnt(8)
	ds_write_b128 v172, v[212:215]
	s_branch .LBB0_70
